# attention unit prologue: first K/V tile fetch issued together with the Q loads (one round trip instead of two)
# speedup vs baseline: 1.0071x; 1.0071x over previous
; __device__ __forceinline__ void unpack8(u32x4v w, float* f) { f[0] = bflo(w.x); f[1] = bfhi(w.x); f[2] = bflo(w.y); f[3] = bfhi(w.y); f[4] = bflo(w.z); f[5] = bfhi(w.z); f[6] = bflo(w.w); f[7] = bfhi(w.w); }
; #define ATT_FETCH(KT) do { _Pragma("unroll") for (int hh = 0; hh < 2; ++hh) { const bf16* krow = P + (seq0 + 128 * (KT) + 64 * hh + skey) * PW; \
;         gk0[hh] = *(const u32x4v*)(krow + KC + part * 16); gk1[hh] = *(const u32x4v*)(krow + KC + part * 16 + 8); \
;         gv0[hh] = *(const u32x4v*)(krow + VC + part * 16); gv1[hh] = *(const u32x4v*)(krow + VC + part * 16 + 8); } } while (0)
; __device__ __forceinline__ void attn_unit(const Args& c, int l, int b, int h, int qb, float lam, float lam_init, LAS unsigned char* lds) {
;     ...
;         const bf16* qrow = P + (seq0 + 128 * qb + 16 * w + r) * PW + QC;
; #pragma unroll
;         for (int m = 0; m < 2; ++m) {
;             float f[16];
;             unpack8(*(const u32x4v*)(qrow + m * 64 + q4 * 8), f); unpack8(*(const u32x4v*)(qrow + m * 64 + 32 + q4 * 8), f + 8);
;             float ss = 0.f;
; #pragma unroll
;             for (int e = 0; e < 16; ++e) ss += f[e] * f[e];
;             ss += __shfl_xor(ss, 16); ss += __shfl_xor(ss, 32);
;             const float sc = rsqrtf(ss * (1.f / 64.f) + 1e-6f) * (0.125f * 1.4426950408889634f);
;     ...
;     ATT_FETCH(0);
.Lattn_prio_skip:
	s_add_u32 s12, s8, s30
	s_addc_u32 s13, s9, s31
	s_ashr_i32 s4, s4, 2
	s_lshl_b32 s7, s22, 7
	s_and_b32 s8, s4, -16
	s_add_i32 s5, s7, s18
	s_ashr_i32 s4, s8, 31
	s_add_u32 s5, s8, s5
	v_or_b32_e32 v184, s5, v107
	s_addc_u32 s9, s4, 0
	v_mad_u64_u32 v[2:3], s[4:5], v184, s27, v[18:19]
	v_mad_i32_i24 v3, s9, v196, v3
	s_lshl_b32 s4, s19, 1
	s_mov_b32 s5, s15
	v_lshl_add_u64 v[2:3], v[2:3], 0, s[4:5]
	v_lshlrev_b32_e32 v0, 4, v108
	v_lshl_add_u64 v[2:3], v[2:3], 0, v[0:1]
	s_movk_i32 s5, 0x1000
	v_add_co_u32_e32 v2, vcc, s5, v2
	v_lshlrev_b32_e32 v14, 5, v108
	s_nop 0
	v_addc_co_u32_e32 v3, vcc, 0, v3, vcc
	flat_load_dwordx4 v[26:29], v[2:3] offset:3904
	flat_load_dwordx4 v[30:33], v[2:3] offset:4032
	flat_load_dwordx4 v[34:37], v[2:3] offset:3840
	flat_load_dwordx4 v[38:41], v[2:3] offset:3968
	s_nop 0
	global_load_dwordx4 v[2:5], v14, s[12:13] offset:144
	global_load_dwordx4 v[6:9], v14, s[12:13] offset:128
	global_load_dwordx4 v[10:13], v14, s[12:13] offset:16
	s_nop 0
	global_load_dwordx4 v[14:17], v14, s[12:13]
	v_ashrrev_i32_e32 v186, 3, v106
	s_lshl_b32 s20, s0, 1
	s_mov_b32 s21, s15
	s_lshl_b32 s28, s1, 1
	s_mov_b32 s29, s15
	v_lshlrev_b32_e32 v126, 4, v106
	v_add_u32_e32 v127, s18, v186
	v_and_b32_e32 v126, 0x70, v126
	v_mad_i64_i32 v[128:129], s[12:13], v127, s27, v[18:19]
	v_lshlrev_b32_e32 v130, 1, v126
	v_mov_b32_e32 v131, 0
	v_lshl_add_u64 v[132:133], v[128:129], 0, s[20:21]
	v_lshl_add_u64 v[128:129], v[128:129], 0, s[28:29]
	v_lshl_add_u64 v[132:133], v[132:133], 0, v[130:131]
	v_lshl_add_u64 v[128:129], v[128:129], 0, v[130:131]
	global_load_dwordx4 v[110:113], v[132:133], off
	global_load_dwordx4 v[114:117], v[132:133], off offset:16
	global_load_dwordx4 v[118:121], v[128:129], off
	global_load_dwordx4 v[122:125], v[128:129], off offset:16
	v_add_u32_e32 v127, 64, v127
	v_mad_i64_i32 v[128:129], s[12:13], v127, s27, v[18:19]
	v_lshl_add_u64 v[132:133], v[128:129], 0, s[20:21]
	v_lshl_add_u64 v[128:129], v[128:129], 0, s[28:29]
	v_lshl_add_u64 v[132:133], v[132:133], 0, v[130:131]
	v_lshl_add_u64 v[128:129], v[128:129], 0, v[130:131]
	global_load_dwordx4 v[90:93], v[132:133], off
	global_load_dwordx4 v[94:97], v[132:133], off offset:16
	global_load_dwordx4 v[98:101], v[128:129], off
	global_load_dwordx4 v[102:105], v[128:129], off offset:16
	s_add_u32 s10, s10, s30
	s_addc_u32 s11, s11, s31
	v_lshlrev_b32_e32 v208, 2, v108
	s_add_i32 s8, s8, s7
	s_movk_i32 s7, 0x110
	v_or_b32_e32 v209, s8, v107
	v_mov_b32_e32 v108, v1
	v_mov_b32_e32 v109, v1
	s_mov_b32 s5, 0
	v_mov_b32_e32 v185, s9
	v_ashrrev_i32_e32 v187, 31, v186
	s_sub_i32 s34, 16, s6
	v_mov_b32_e32 v216, 0
	v_mov_b32_e32 v192, 0xff800000
	v_mov_b32_e32 v148, 0xff800000
	v_mov_b32_e32 v215, 0
	s_mov_b32 s35, 0
	s_waitcnt vmcnt(0) lgkmcnt(0)
	v_lshlrev_b32_e32 v42, 16, v29
	v_and_b32_e32 v43, 0xffff0000, v29
	v_lshlrev_b32_e32 v20, 16, v33
	v_and_b32_e32 v21, 0xffff0000, v33
	v_lshlrev_b32_e32 v44, 16, v28
	v_and_b32_e32 v45, 0xffff0000, v28
	v_lshlrev_b32_e32 v22, 16, v32
	v_and_b32_e32 v23, 0xffff0000, v32
	v_lshlrev_b32_e32 v28, 16, v27
	v_and_b32_e32 v29, 0xffff0000, v27
	v_lshlrev_b32_e32 v24, 16, v31
	v_and_b32_e32 v25, 0xffff0000, v31
	v_lshlrev_b32_e32 v32, 16, v26
	v_and_b32_e32 v33, 0xffff0000, v26
	v_lshlrev_b32_e32 v26, 16, v30
	v_and_b32_e32 v27, 0xffff0000, v30
	v_lshlrev_b32_e32 v30, 16, v37
	v_and_b32_e32 v31, 0xffff0000, v37
	v_lshlrev_b32_e32 v46, 16, v41
	v_and_b32_e32 v47, 0xffff0000, v41
	v_lshlrev_b32_e32 v48, 16, v36
	v_and_b32_e32 v49, 0xffff0000, v36
	v_lshlrev_b32_e32 v36, 16, v40
	v_and_b32_e32 v37, 0xffff0000, v40
	v_lshlrev_b32_e32 v40, 16, v35
	v_and_b32_e32 v41, 0xffff0000, v35
	v_and_b32_e32 v51, 0xffff0000, v34
	v_and_b32_e32 v35, 0xffff0000, v38
	v_lshlrev_b32_e32 v50, 16, v34
	v_lshlrev_b32_e32 v34, 16, v38
	v_mov_b32_e32 v82, v35
	v_mov_b32_e32 v83, v51
	v_lshlrev_b32_e32 v58, 16, v39
	v_mov_b32_e32 v80, v34
	v_mov_b32_e32 v81, v50
	v_pk_mul_f32 v[82:83], v[82:83], v[82:83]
	v_and_b32_e32 v59, 0xffff0000, v39
	v_mov_b32_e32 v76, v58
	v_mov_b32_e32 v77, v40
	v_pk_fma_f32 v[80:81], v[80:81], v[80:81], v[82:83]
	v_mov_b32_e32 v78, v59
	v_mov_b32_e32 v79, v41
	v_pk_fma_f32 v[76:77], v[76:77], v[76:77], v[80:81]
	v_mov_b32_e32 v72, v36
	v_mov_b32_e32 v73, v48
	v_pk_fma_f32 v[76:77], v[78:79], v[78:79], v[76:77]
	v_mov_b32_e32 v74, v37
	v_mov_b32_e32 v75, v49
	v_pk_fma_f32 v[72:73], v[72:73], v[72:73], v[76:77]
	v_mov_b32_e32 v68, v46
	v_mov_b32_e32 v69, v30
	v_pk_fma_f32 v[72:73], v[74:75], v[74:75], v[72:73]
	v_pk_mul_f32 v[64:65], v[32:33], v[32:33]
	v_pk_mul_f32 v[66:67], v[26:27], v[26:27]
	v_mov_b32_e32 v70, v47
	v_mov_b32_e32 v71, v31
	v_pk_fma_f32 v[68:69], v[68:69], v[68:69], v[72:73]
	v_pk_mul_f32 v[60:61], v[28:29], v[28:29]
	v_pk_fma_f32 v[68:69], v[70:71], v[70:71], v[68:69]
	v_mov_b32_e32 v70, v66
	v_mov_b32_e32 v71, v64
	v_pk_mul_f32 v[62:63], v[24:25], v[24:25]
	v_pk_add_f32 v[68:69], v[70:71], v[68:69]
	v_mov_b32_e32 v64, v67
	v_pk_add_f32 v[64:65], v[64:65], v[68:69]
	v_mov_b32_e32 v66, v62
	v_mov_b32_e32 v67, v60
	v_pk_mul_f32 v[54:55], v[44:45], v[44:45]
	v_pk_mul_f32 v[56:57], v[22:23], v[22:23]
	v_pk_add_f32 v[64:65], v[66:67], v[64:65]
	v_mov_b32_e32 v60, v63
	v_pk_add_f32 v[60:61], v[60:61], v[64:65]
	v_mov_b32_e32 v62, v56
	v_mov_b32_e32 v63, v54
	v_pk_mul_f32 v[38:39], v[42:43], v[42:43]
	v_pk_mul_f32 v[52:53], v[20:21], v[20:21]
	v_pk_add_f32 v[60:61], v[62:63], v[60:61]
	v_mov_b32_e32 v54, v57
	v_pk_add_f32 v[54:55], v[54:55], v[60:61]
	v_mov_b32_e32 v56, v52
	v_mov_b32_e32 v57, v38
	v_pk_add_f32 v[54:55], v[56:57], v[54:55]
	v_mov_b32_e32 v38, v53
	v_pk_add_f32 v[38:39], v[38:39], v[54:55]
	ds_bpermute_b32 v53, v205, v39
	ds_bpermute_b32 v52, v205, v38
	s_waitcnt lgkmcnt(0)
; __device__ __forceinline__ unsigned pk2(float lo, float hi) { f32x2_t v = {lo, hi}; bf16x2_t b = __builtin_convertvector(v, bf16x2_t); return __builtin_bit_cast(unsigned, b); }
; #define ATT_FETCH(KT) do { _Pragma("unroll") for (int hh = 0; hh < 2; ++hh) { const bf16* krow = P + (seq0 + 128 * (KT) + 64 * hh + skey) * PW; \
;         gk0[hh] = *(const u32x4v*)(krow + KC + part * 16); gk1[hh] = *(const u32x4v*)(krow + KC + part * 16 + 8); \
;         gv0[hh] = *(const u32x4v*)(krow + VC + part * 16); gv1[hh] = *(const u32x4v*)(krow + VC + part * 16 + 8); } } while (0)
; __device__ __forceinline__ void attn_unit(const Args& c, int l, int b, int h, int qb, float lam, float lam_init, LAS unsigned char* lds) {
;     ...
;             ss += __shfl_xor(ss, 16); ss += __shfl_xor(ss, 32);
;             const float sc = rsqrtf(ss * (1.f / 64.f) + 1e-6f) * (0.125f * 1.4426950408889634f);
; #pragma unroll
;             for (int ks = 0; ks < 2; ++ks) { u32x4v o; const float* g = f + 8 * ks; const float* wn = qnw + ks * 32 + q4 * 8;
;                 o.x = pk2(g[0] * sc * wn[0], g[1] * sc * wn[1]); o.y = pk2(g[2] * sc * wn[2], g[3] * sc * wn[3]); o.z = pk2(g[4] * sc * wn[4], g[5] * sc * wn[5]); o.w = pk2(g[6] * sc * wn[6], g[7] * sc * wn[7]);
;                 qf[m][ks] = __builtin_bit_cast(bf16x8, o); }
;         }
;     }
;     f32x4 O[2][8];
; #pragma unroll
;     for (int m = 0; m < 2; ++m)
; #pragma unroll
;         for (int vb = 0; vb < 8; ++vb) O[m][vb] = (f32x4){0.f, 0.f, 0.f, 0.f};
;     float mrow[2] = {-INFINITY, -INFINITY}, lrow[2] = {0.f, 0.f};
;     const int NT = qb + 1;
;     const int skey = tid >> 3, part = tid & 7;
;     const float* kwp = knw + (part & 3) * 16;
;     u32x4v gk0[2], gk1[2], gv0[2], gv1[2];
;     ...
;     ATT_FETCH(0);
	v_pk_add_f32 v[38:39], v[38:39], v[52:53]
	ds_bpermute_b32 v53, v206, v39
	ds_bpermute_b32 v52, v206, v38
	s_waitcnt lgkmcnt(0)
	v_pk_add_f32 v[38:39], v[38:39], v[52:53]
	s_nop 0
	v_pk_fma_f32 v[38:39], v[38:39], s[26:27], v[178:179] op_sel_hi:[1,0,0]
	s_nop 0
	v_mul_f32_e32 v52, 0x4b800000, v39
	v_cmp_gt_f32_e32 vcc, s33, v39
	s_nop 1
	v_cndmask_b32_e32 v39, v39, v52, vcc
	v_rsq_f32_e32 v39, v39
	s_nop 0
	v_mul_f32_e32 v52, 0x45800000, v39
	v_cndmask_b32_e32 v39, v39, v52, vcc
	v_mul_f32_e32 v52, 0x3e38aa3b, v39
	v_pk_mul_f32 v[28:29], v[52:53], v[28:29] op_sel_hi:[0,1]
	v_pk_mul_f32 v[32:33], v[52:53], v[32:33] op_sel_hi:[0,1]
	v_pk_mul_f32 v[28:29], v[8:9], v[28:29]
	v_pk_mul_f32 v[60:61], v[52:53], v[50:51] op_sel_hi:[0,1]
	v_pk_mul_f32 v[30:31], v[52:53], v[30:31] op_sel_hi:[0,1]
	v_pk_mul_f32 v[42:43], v[52:53], v[42:43] op_sel_hi:[0,1]
	v_cvt_pk_bf16_f32 v51, v28, v29
	v_pk_mul_f32 v[28:29], v[6:7], v[32:33]
	v_pk_mul_f32 v[48:49], v[52:53], v[48:49] op_sel_hi:[0,1]
	v_pk_mul_f32 v[44:45], v[52:53], v[44:45] op_sel_hi:[0,1]
	v_pk_mul_f32 v[42:43], v[4:5], v[42:43]
	v_cvt_pk_bf16_f32 v50, v28, v29
	v_pk_mul_f32 v[28:29], v[12:13], v[30:31]
	v_lshlrev_b32_e32 v30, 4, v106
	v_add_u32_e32 v39, s18, v186
	v_pk_mul_f32 v[40:41], v[52:53], v[40:41] op_sel_hi:[0,1]
	v_cvt_pk_bf16_f32 v53, v42, v43
	v_pk_mul_f32 v[42:43], v[2:3], v[44:45]
	v_cvt_pk_bf16_f32 v57, v28, v29
	v_pk_mul_f32 v[28:29], v[10:11], v[48:49]
	v_and_b32_e32 v30, 0x70, v30
	v_mad_i64_i32 v[32:33], s[12:13], v39, s27, v[18:19]
	v_cvt_pk_bf16_f32 v52, v42, v43
	v_cvt_pk_bf16_f32 v56, v28, v29
	v_pk_mul_f32 v[28:29], v[16:17], v[40:41]
	v_lshl_add_u64 v[40:41], v[32:33], 0, s[20:21]
	v_lshlrev_b32_e32 v42, 1, v30
	v_mov_b32_e32 v43, v1
	v_lshl_add_u64 v[32:33], v[32:33], 0, s[28:29]
	v_lshl_add_u64 v[40:41], v[40:41], 0, v[42:43]
	v_lshl_add_u64 v[32:33], v[32:33], 0, v[42:43]
	v_mov_b64_e32 v[66:67], v[110:111]
	v_mov_b64_e32 v[68:69], v[112:113]
	v_mov_b64_e32 v[70:71], v[114:115]
	v_mov_b64_e32 v[72:73], v[116:117]
	v_mov_b64_e32 v[78:79], v[118:119]
	v_mov_b64_e32 v[80:81], v[120:121]
	v_mov_b64_e32 v[82:83], v[122:123]
	v_mov_b64_e32 v[84:85], v[124:125]
	v_add_u32_e32 v32, 64, v39
	v_mad_i64_i32 v[18:19], s[12:13], v32, s27, v[18:19]
	v_lshl_add_u64 v[32:33], v[18:19], 0, s[20:21]
	v_lshl_add_u64 v[18:19], v[18:19], 0, s[28:29]
	v_lshl_add_u64 v[32:33], v[32:33], 0, v[42:43]
	v_lshl_add_u64 v[18:19], v[18:19], 0, v[42:43]
	v_mul_f32_e32 v31, 0x4b800000, v38
	v_cmp_gt_f32_e32 vcc, s33, v38
	v_cvt_pk_bf16_f32 v55, v28, v29
	s_nop 0
	v_cndmask_b32_e32 v18, v38, v31, vcc
	v_rsq_f32_e32 v31, v18
	v_pk_mul_f32 v[18:19], v[14:15], v[60:61]
	s_nop 0
	v_cvt_pk_bf16_f32 v54, v18, v19
	v_mul_f32_e32 v18, 0x45800000, v31
	v_cndmask_b32_e32 v18, v31, v18, vcc
	v_mul_f32_e32 v18, 0x3e38aa3b, v18
	v_pk_mul_f32 v[28:29], v[18:19], v[34:35] op_sel_hi:[0,1]
	v_pk_mul_f32 v[14:15], v[14:15], v[28:29]
	s_nop 0
	v_cvt_pk_bf16_f32 v74, v14, v15
	v_pk_mul_f32 v[14:15], v[18:19], v[58:59] op_sel_hi:[0,1]
	v_pk_mul_f32 v[14:15], v[16:17], v[14:15]
	s_nop 0
	v_cvt_pk_bf16_f32 v75, v14, v15
	v_pk_mul_f32 v[14:15], v[18:19], v[36:37] op_sel_hi:[0,1]
	v_pk_mul_f32 v[10:11], v[10:11], v[14:15]
	s_nop 0
	v_cvt_pk_bf16_f32 v76, v10, v11
	v_pk_mul_f32 v[10:11], v[18:19], v[46:47] op_sel_hi:[0,1]
	v_pk_mul_f32 v[10:11], v[12:13], v[10:11]
	s_nop 0
	v_cvt_pk_bf16_f32 v77, v10, v11
	v_pk_mul_f32 v[10:11], v[18:19], v[26:27] op_sel_hi:[0,1]
	v_pk_mul_f32 v[6:7], v[6:7], v[10:11]
	s_nop 0
	v_cvt_pk_bf16_f32 v86, v6, v7
	v_pk_mul_f32 v[6:7], v[18:19], v[24:25] op_sel_hi:[0,1]
	v_pk_mul_f32 v[6:7], v[8:9], v[6:7]
	s_nop 0
	v_cvt_pk_bf16_f32 v87, v6, v7
	v_pk_mul_f32 v[6:7], v[18:19], v[22:23] op_sel_hi:[0,1]
	v_pk_mul_f32 v[2:3], v[2:3], v[6:7]
	s_nop 0
	v_cvt_pk_bf16_f32 v88, v2, v3
	v_pk_mul_f32 v[2:3], v[18:19], v[20:21] op_sel_hi:[0,1]
	v_pk_mul_f32 v[2:3], v[4:5], v[2:3]
	s_nop 0
	v_cvt_pk_bf16_f32 v89, v2, v3
	v_lshlrev_b32_e32 v2, 6, v106
	v_and_b32_e32 v2, 0xc0, v2
	v_mov_b32_e32 v3, v1
	v_lshl_add_u64 v[188:189], s[10:11], 0, v[2:3]
	v_bfe_u32 v2, v106, 2, 2
	v_add_u32_e32 v3, 0, v0
	v_or_b32_e32 v0, v208, v2
	v_lshlrev_b32_e32 v2, 3, v106
	v_mul_u32_u24_e32 v0, 0x110, v0
	v_and_b32_e32 v2, 24, v2
	v_add3_u32 v210, 0, v0, v2
	v_mul_lo_u32 v0, v186, s7
	v_mul_u32_u24_e32 v2, 0x110, v107
	v_mov_b32_e32 v106, v1
	v_mov_b32_e32 v107, v1
	v_add3_u32 v211, 0, v42, v0
	v_lshlrev_b32_e32 v0, 1, v30
	v_add_u32_e32 v212, v3, v2
	v_mov_b64_e32 v[2:3], v[106:107]
	v_mov_b64_e32 v[10:11], v[106:107]
	v_mov_b64_e32 v[18:19], v[106:107]
	v_mov_b64_e32 v[58:59], v[106:107]
	v_mov_b64_e32 v[26:27], v[106:107]
	v_mov_b64_e32 v[34:35], v[106:107]
	v_mov_b64_e32 v[42:43], v[106:107]
	v_mov_b64_e32 v[112:113], v[108:109]
	v_mov_b64_e32 v[6:7], v[106:107]
	v_mov_b64_e32 v[14:15], v[106:107]
	v_mov_b64_e32 v[22:23], v[106:107]
	v_mov_b64_e32 v[62:63], v[106:107]
	v_mov_b64_e32 v[30:31], v[106:107]
	v_mov_b64_e32 v[38:39], v[106:107]
	v_mov_b64_e32 v[46:47], v[106:107]
	v_mov_b64_e32 v[4:5], v[108:109]
	v_mov_b64_e32 v[12:13], v[108:109]
	v_mov_b64_e32 v[20:21], v[108:109]
	v_mov_b64_e32 v[60:61], v[108:109]
	v_mov_b64_e32 v[28:29], v[108:109]
	v_mov_b64_e32 v[36:37], v[108:109]
	v_mov_b64_e32 v[44:45], v[108:109]
	v_mov_b64_e32 v[110:111], v[106:107]
	v_mov_b64_e32 v[8:9], v[108:109]
	v_mov_b64_e32 v[16:17], v[108:109]
	v_mov_b64_e32 v[24:25], v[108:109]
	v_mov_b64_e32 v[64:65], v[108:109]
	v_mov_b64_e32 v[32:33], v[108:109]
	v_mov_b64_e32 v[40:41], v[108:109]
	v_mov_b64_e32 v[48:49], v[108:109]
